# v100 + software prefetch of the next iteration's x rows in the P0 rmsnorm loop (second register set, one counted wait at the loop bottom)
# baseline (speedup 1.0000x reference)
; __device__ __forceinline__ void p0_prologue(const Ptrs& P, LAS unsigned char* lds, int vcu, int G) {
;     ...
;     for (int m = gw; m < TT; m += 2 * NGW) {
;         const int m2 = (m + NGW < TT) ? m + NGW : m;
;         const f32x4* xr = (const f32x4*)(P.x + (size_t)m * DM) + lane; const f32x4* xr2 = (const f32x4*)(P.x + (size_t)m2 * DM) + lane; f32x4 v[4], v2[4]; float s = 0.f, s2 = 0.f;
; #pragma unroll
;         for (int j = 0; j < 4; ++j) { v[j] = xr[64 * j]; v2[j] = xr2[64 * j]; }
; #pragma unroll
;         for (int j = 0; j < 4; ++j) { s += (v[j].x * v[j].x + v[j].y * v[j].y) + (v[j].z * v[j].z + v[j].w * v[j].w); s2 += (v2[j].x * v2[j].x + v2[j].y * v2[j].y) + (v2[j].z * v2[j].z + v2[j].w * v2[j].w); }
;         const float rstd = rsqrtf(wave_sum(s) * (1.0f / DM) + NORM_EPS), rstd2 = rsqrtf(wave_sum(s2) * (1.0f / DM) + NORM_EPS);
.LBB0_55:
	s_cmpk_gt_i32 s0, 0x3fff
	s_cbranch_scc1 .LBB0_58
	v_mbcnt_lo_u32_b32 v6, -1, 0
	v_mbcnt_hi_u32_b32 v6, -1, v6
	v_and_b32_e32 v7, 64, v6
	v_add_u32_e32 v12, 64, v7
	v_xor_b32_e32 v7, 1, v6
	v_cmp_lt_i32_e32 vcc, v7, v12
	v_xor_b32_e32 v8, 2, v6
	v_xor_b32_e32 v9, 4, v6
	v_cndmask_b32_e32 v7, v6, v7, vcc
	v_cmp_lt_i32_e32 vcc, v8, v12
	v_xor_b32_e32 v10, 8, v6
	v_xor_b32_e32 v11, 16, v6
	v_cndmask_b32_e32 v8, v6, v8, vcc
	v_cmp_lt_i32_e32 vcc, v9, v12
	v_xor_b32_e32 v13, 32, v6
	v_lshlrev_b32_e32 v4, 3, v25
	v_cndmask_b32_e32 v9, v6, v9, vcc
	v_cmp_lt_i32_e32 vcc, v10, v12
	v_mov_b32_e32 v5, 0
	v_lshl_add_u64 v[0:1], s[78:79], 0, v[4:5]
	v_cndmask_b32_e32 v10, v6, v10, vcc
	v_cmp_lt_i32_e32 vcc, v11, v12
	s_mov_b64 s[6:7], 0x2000000
	v_lshlrev_b32_e32 v4, 4, v25
	v_cndmask_b32_e32 v11, v6, v11, vcc
	v_cmp_lt_i32_e32 vcc, v13, v12
	v_lshl_add_u64 v[0:1], v[0:1], 0, s[6:7]
	s_waitcnt lgkmcnt(0)
	v_lshl_add_u64 v[2:3], s[56:57], 0, v[4:5]
	v_cndmask_b32_e32 v6, v6, v13, vcc
	v_lshl_add_u64 v[4:5], s[60:61], 0, v[4:5]
	v_lshlrev_b32_e32 v7, 2, v7
	v_lshlrev_b32_e32 v8, 2, v8
	v_lshlrev_b32_e32 v9, 2, v9
	v_lshlrev_b32_e32 v10, 2, v10
	v_lshlrev_b32_e32 v11, 2, v11
	v_lshlrev_b32_e32 v12, 2, v6
	s_mov_b32 s6, 0x3a800000
	v_mov_b32_e32 v6, 0x358637bd
	s_mov_b32 s7, 0x800000
	global_load_dwordx4 v[100:103], v[4:5], off
	global_load_dwordx4 v[104:107], v[4:5], off offset:1024
	global_load_dwordx4 v[108:111], v[4:5], off offset:2048
	global_load_dwordx4 v[112:115], v[4:5], off offset:3072
	s_add_i32 s14, s0, s17
	s_cmpk_lt_i32 s14, 0x4000
	s_cselect_b32 s14, s14, s0
	s_ashr_i32 s13, s0, 31
	s_mov_b32 s12, s0
	s_lshl_b64 s[12:13], s[12:13], 12
	v_lshl_add_u64 v[22:23], v[2:3], 0, s[12:13]
	global_load_dwordx4 v[120:123], v[22:23], off nt
	global_load_dwordx4 v[124:127], v[22:23], off offset:1024 nt
	global_load_dwordx4 v[128:131], v[22:23], off offset:3072 nt
	global_load_dwordx4 v[132:135], v[22:23], off offset:2048 nt
	s_ashr_i32 s13, s14, 31
	s_mov_b32 s12, s14
	s_lshl_b64 s[12:13], s[12:13], 12
	v_lshl_add_u64 v[22:23], v[2:3], 0, s[12:13]
	global_load_dwordx4 v[136:139], v[22:23], off nt
	global_load_dwordx4 v[140:143], v[22:23], off offset:1024 nt
	global_load_dwordx4 v[144:147], v[22:23], off offset:3072 nt
	global_load_dwordx4 v[148:151], v[22:23], off offset:2048 nt
	s_waitcnt vmcnt(0)
.LBB0_57:
	s_add_i32 s8, s0, s17
	s_cmpk_lt_i32 s8, 0x4000
	s_cselect_b32 s10, s8, s0
	s_ashr_i32 s1, s0, 31
	s_ashr_i32 s11, s10, 31
	v_mov_b32_e32 v18, v120
	v_mov_b32_e32 v19, v121
	v_mov_b32_e32 v20, v122
	v_mov_b32_e32 v21, v123
	v_mov_b32_e32 v26, v124
	v_mov_b32_e32 v27, v125
	v_mov_b32_e32 v28, v126
	v_mov_b32_e32 v29, v127
	v_mov_b32_e32 v30, v128
	v_mov_b32_e32 v31, v129
	v_mov_b32_e32 v32, v130
	v_mov_b32_e32 v33, v131
	v_mov_b32_e32 v34, v132
	v_mov_b32_e32 v35, v133
	v_mov_b32_e32 v36, v134
	v_mov_b32_e32 v37, v135
	v_mov_b32_e32 v38, v136
	v_mov_b32_e32 v39, v137
	v_mov_b32_e32 v40, v138
	v_mov_b32_e32 v41, v139
	v_mov_b32_e32 v42, v140
	v_mov_b32_e32 v43, v141
	v_mov_b32_e32 v44, v142
	v_mov_b32_e32 v45, v143
	v_mov_b32_e32 v46, v144
	v_mov_b32_e32 v47, v145
	v_mov_b32_e32 v48, v146
	v_mov_b32_e32 v49, v147
	v_mov_b32_e32 v50, v148
	v_mov_b32_e32 v51, v149
	v_mov_b32_e32 v52, v150
	v_mov_b32_e32 v53, v151
	s_add_i32 s9, s8, s17
	s_cmpk_lt_i32 s9, 0x4000
	s_cselect_b32 s9, s9, s0
	s_add_i32 s14, s9, s17
	s_cmpk_lt_i32 s14, 0x4000
	s_cselect_b32 s14, s14, s9
	s_ashr_i32 s13, s9, 31
	s_mov_b32 s12, s9
	s_lshl_b64 s[12:13], s[12:13], 12
	v_lshl_add_u64 v[22:23], v[2:3], 0, s[12:13]
	global_load_dwordx4 v[120:123], v[22:23], off nt
	global_load_dwordx4 v[124:127], v[22:23], off offset:1024 nt
	global_load_dwordx4 v[128:131], v[22:23], off offset:3072 nt
	global_load_dwordx4 v[132:135], v[22:23], off offset:2048 nt
	s_ashr_i32 s13, s14, 31
	s_mov_b32 s12, s14
	s_lshl_b64 s[12:13], s[12:13], 12
	v_lshl_add_u64 v[22:23], v[2:3], 0, s[12:13]
	global_load_dwordx4 v[136:139], v[22:23], off nt
	global_load_dwordx4 v[140:143], v[22:23], off offset:1024 nt
	global_load_dwordx4 v[144:147], v[22:23], off offset:3072 nt
	global_load_dwordx4 v[148:151], v[22:23], off offset:2048 nt
	s_lshl_b64 s[0:1], s[0:1], 11
	v_lshl_add_u64 v[54:55], v[0:1], 0, s[0:1]
	s_lshl_b64 s[0:1], s[10:11], 11
	v_lshl_add_u64 v[56:57], v[0:1], 0, s[0:1]
	v_pk_mul_f32 v[22:23], v[20:21], v[20:21]
	v_pk_mul_f32 v[58:59], v[18:19], v[18:19]
	v_pk_mul_f32 v[60:61], v[28:29], v[28:29]
	v_pk_mul_f32 v[62:63], v[26:27], v[26:27]
	v_mul_f32_e32 v64, v35, v35
	v_mul_f32_e32 v66, v37, v37
	v_pk_mov_b32 v[68:69], v[58:59], v[22:23] op_sel:[1,0]
	v_mov_b32_e32 v59, v23
	v_pk_mul_f32 v[22:23], v[40:41], v[40:41]
	v_pk_mul_f32 v[70:71], v[38:39], v[38:39]
	v_pk_mov_b32 v[72:73], v[62:63], v[60:61] op_sel:[1,0]
	v_mov_b32_e32 v63, v61
	v_pk_mul_f32 v[60:61], v[44:45], v[44:45]
	v_pk_mul_f32 v[74:75], v[42:43], v[42:43]
	v_mul_f32_e32 v77, v32, v32
	v_mul_f32_e32 v79, v33, v33
	v_pk_fma_f32 v[64:65], v[34:35], v[34:35], v[64:65] op_sel_hi:[1,1,0]
	v_pk_fma_f32 v[66:67], v[36:37], v[36:37], v[66:67] op_sel_hi:[1,1,0]
	v_pk_add_f32 v[58:59], v[68:69], v[58:59]
	v_pk_mov_b32 v[68:69], v[70:71], v[22:23] op_sel:[1,0]
	v_mov_b32_e32 v71, v23
	v_pk_add_f32 v[22:23], v[72:73], v[62:63]
	v_pk_mov_b32 v[62:63], v[74:75], v[60:61] op_sel:[1,0]
	v_mov_b32_e32 v75, v61
	v_mul_f32_e32 v76, v51, v51
	v_mul_f32_e32 v78, v53, v53
	v_mov_b32_e32 v65, v77
	v_mov_b32_e32 v67, v79
	v_pk_add_f32 v[68:69], v[68:69], v[70:71]
	v_pk_add_f32 v[62:63], v[62:63], v[74:75]
	v_mul_f32_e32 v13, v30, v30
	v_mul_f32_e32 v25, v31, v31
	v_mul_f32_e32 v80, v46, v46
	v_mul_f32_e32 v81, v47, v47
	v_mul_f32_e32 v82, v48, v48
	v_mul_f32_e32 v83, v49, v49
	v_pk_fma_f32 v[60:61], v[50:51], v[50:51], v[76:77] op_sel_hi:[1,1,0]
	v_pk_fma_f32 v[72:73], v[52:53], v[52:53], v[78:79] op_sel_hi:[1,1,0]
	v_pk_add_f32 v[58:59], v[58:59], v[58:59] op_sel:[0,1] op_sel_hi:[1,0]
	v_pk_add_f32 v[22:23], v[22:23], v[22:23] op_sel:[0,1] op_sel_hi:[1,0]
	v_pk_add_f32 v[64:65], v[64:65], v[66:67]
	v_pk_add_f32 v[66:67], v[68:69], v[68:69] op_sel:[0,1] op_sel_hi:[1,0]
	v_pk_add_f32 v[62:63], v[62:63], v[62:63] op_sel:[0,1] op_sel_hi:[1,0]
	v_mov_b32_e32 v61, v82
	v_mov_b32_e32 v73, v83
	v_mov_b32_e32 v59, v13
	v_mov_b32_e32 v23, v25
	v_mov_b32_e32 v67, v80
	v_mov_b32_e32 v63, v81
	v_pk_add_f32 v[60:61], v[60:61], v[72:73]
	v_pk_add_f32 v[22:23], v[58:59], v[22:23]
	v_pk_add_f32 v[58:59], v[66:67], v[62:63]
	v_pk_add_f32 v[22:23], v[22:23], v[64:65]
	v_pk_add_f32 v[58:59], v[58:59], v[60:61]
	v_mov_b32_e32 v61, v22
	v_mov_b32_e32 v60, v58
	v_mov_b32_e32 v22, v59
	v_pk_add_f32 v[22:23], v[60:61], v[22:23]
	ds_bpermute_b32 v59, v7, v23
	ds_bpermute_b32 v58, v7, v22
	s_waitcnt lgkmcnt(0)
; __device__ __forceinline__ unsigned pk_bf16(float lo, float hi) { typedef __bf16 b2 __attribute__((ext_vector_type(2))); f32x2 v = {lo, hi}; b2 b = __builtin_convertvector(v, b2); return __builtin_bit_cast(unsigned, b); }
; __device__ __forceinline__ void p0_prologue(const Ptrs& P, LAS unsigned char* lds, int vcu, int G) {
;     ...
;         const float rstd = rsqrtf(wave_sum(s) * (1.0f / DM) + NORM_EPS), rstd2 = rsqrtf(wave_sum(s2) * (1.0f / DM) + NORM_EPS);
;         u32x2* o8 = (u32x2*)(H + (size_t)m * DM) + lane; u32x2* o82 = (u32x2*)(H + (size_t)m2 * DM) + lane;
; #pragma unroll
;         for (int j = 0; j < 4; ++j) { const f32x4 w4 = ((const f32x4*)P.norm_w)[lane + 64 * j];
;             o8[64 * j] = (u32x2){pk_bf16(v[j].x * rstd * w4.x, v[j].y * rstd * w4.y), pk_bf16(v[j].z * rstd * w4.z, v[j].w * rstd * w4.w)};
;             o82[64 * j] = (u32x2){pk_bf16(v2[j].x * rstd2 * w4.x, v2[j].y * rstd2 * w4.y), pk_bf16(v2[j].z * rstd2 * w4.z, v2[j].w * rstd2 * w4.w)}; }
	v_pk_add_f32 v[22:23], v[22:23], v[58:59]
	ds_bpermute_b32 v59, v8, v23
	ds_bpermute_b32 v58, v8, v22
	s_waitcnt lgkmcnt(0)
	v_pk_add_f32 v[22:23], v[22:23], v[58:59]
	ds_bpermute_b32 v59, v9, v23
	ds_bpermute_b32 v58, v9, v22
	s_waitcnt lgkmcnt(0)
	v_pk_add_f32 v[22:23], v[22:23], v[58:59]
	ds_bpermute_b32 v59, v10, v23
	ds_bpermute_b32 v58, v10, v22
	s_waitcnt lgkmcnt(0)
	v_pk_add_f32 v[22:23], v[22:23], v[58:59]
	ds_bpermute_b32 v59, v11, v23
	ds_bpermute_b32 v58, v11, v22
	s_waitcnt lgkmcnt(0)
	v_pk_add_f32 v[22:23], v[22:23], v[58:59]
	ds_bpermute_b32 v59, v12, v23
	ds_bpermute_b32 v58, v12, v22
	s_waitcnt lgkmcnt(0)
	v_pk_add_f32 v[22:23], v[22:23], v[58:59]
	s_nop 0
	v_pk_fma_f32 v[22:23], v[22:23], s[6:7], v[6:7] op_sel_hi:[1,0,0]
	s_nop 0
	v_mul_f32_e32 v13, 0x4b800000, v23
	v_cmp_gt_f32_e64 s[0:1], s7, v23
	v_mul_f32_e32 v25, 0x4b800000, v22
	v_cmp_gt_f32_e32 vcc, s7, v22
	v_cndmask_b32_e64 v13, v23, v13, s[0:1]
	v_rsq_f32_e32 v13, v13
	v_cndmask_b32_e32 v22, v22, v25, vcc
	v_rsq_f32_e32 v23, v22
	v_mul_f32_e32 v22, 0x45800000, v13
	v_cndmask_b32_e64 v22, v13, v22, s[0:1]
	v_mul_f32_e32 v25, 0x45800000, v23
	v_cndmask_b32_e32 v58, v23, v25, vcc
	v_pk_mul_f32 v[18:19], v[18:19], v[22:23] op_sel_hi:[1,0]
	v_pk_mul_f32 v[20:21], v[20:21], v[22:23] op_sel_hi:[1,0]
	v_pk_mul_f32 v[38:39], v[38:39], v[58:59] op_sel_hi:[1,0]
	v_pk_mul_f32 v[40:41], v[40:41], v[58:59] op_sel_hi:[1,0]
	v_pk_mul_f32 v[18:19], v[100:101], v[18:19]
	v_pk_mul_f32 v[20:21], v[102:103], v[20:21]
	v_pk_mul_f32 v[14:15], v[100:101], v[38:39]
	v_pk_mul_f32 v[16:17], v[102:103], v[40:41]
	v_cvt_pk_bf16_f32 v18, v18, v19
	v_cvt_pk_bf16_f32 v19, v20, v21
	v_cvt_pk_bf16_f32 v14, v14, v15
	v_cvt_pk_bf16_f32 v15, v16, v17
	global_store_dwordx2 v[54:55], v[18:19], off sc1
	global_store_dwordx2 v[56:57], v[14:15], off sc1
	v_pk_mul_f32 v[18:19], v[26:27], v[22:23] op_sel_hi:[1,0]
	v_pk_mul_f32 v[20:21], v[28:29], v[22:23] op_sel_hi:[1,0]
	v_pk_mul_f32 v[26:27], v[42:43], v[58:59] op_sel_hi:[1,0]
	v_pk_mul_f32 v[28:29], v[44:45], v[58:59] op_sel_hi:[1,0]
	s_add_i32 s0, s8, s17
	s_cmpk_gt_i32 s0, 0x3fff
	v_pk_mul_f32 v[18:19], v[104:105], v[18:19]
	v_pk_mul_f32 v[20:21], v[106:107], v[20:21]
	v_pk_mul_f32 v[14:15], v[104:105], v[26:27]
	v_pk_mul_f32 v[16:17], v[106:107], v[28:29]
	v_cvt_pk_bf16_f32 v18, v18, v19
	v_cvt_pk_bf16_f32 v19, v20, v21
	v_cvt_pk_bf16_f32 v14, v14, v15
	v_cvt_pk_bf16_f32 v15, v16, v17
	global_store_dwordx2 v[54:55], v[18:19], off offset:512 sc1
	global_store_dwordx2 v[56:57], v[14:15], off offset:512 sc1
	v_pk_mul_f32 v[18:19], v[34:35], v[22:23] op_sel_hi:[1,0]
	v_pk_mul_f32 v[20:21], v[36:37], v[22:23] op_sel_hi:[1,0]
	v_pk_mul_f32 v[26:27], v[50:51], v[58:59] op_sel_hi:[1,0]
	v_pk_mul_f32 v[28:29], v[52:53], v[58:59] op_sel_hi:[1,0]
	v_pk_mul_f32 v[18:19], v[18:19], v[108:109]
	v_pk_mul_f32 v[20:21], v[20:21], v[110:111]
	v_pk_mul_f32 v[14:15], v[108:109], v[26:27]
	v_pk_mul_f32 v[16:17], v[110:111], v[28:29]
	v_cvt_pk_bf16_f32 v18, v18, v19
	v_cvt_pk_bf16_f32 v19, v20, v21
	v_cvt_pk_bf16_f32 v14, v14, v15
	v_cvt_pk_bf16_f32 v15, v16, v17
	global_store_dwordx2 v[54:55], v[18:19], off offset:1024 sc1
	global_store_dwordx2 v[56:57], v[14:15], off offset:1024 sc1
	v_pk_mul_f32 v[18:19], v[30:31], v[22:23] op_sel_hi:[1,0]
	v_pk_mul_f32 v[20:21], v[32:33], v[22:23] op_sel_hi:[1,0]
	v_pk_mul_f32 v[22:23], v[46:47], v[58:59] op_sel_hi:[1,0]
	v_pk_mul_f32 v[26:27], v[48:49], v[58:59] op_sel_hi:[1,0]
	v_pk_mul_f32 v[18:19], v[18:19], v[112:113]
	v_pk_mul_f32 v[20:21], v[20:21], v[114:115]
	v_pk_mul_f32 v[14:15], v[22:23], v[112:113]
	v_pk_mul_f32 v[16:17], v[26:27], v[114:115]
	v_cvt_pk_bf16_f32 v18, v18, v19
	v_cvt_pk_bf16_f32 v19, v20, v21
	v_cvt_pk_bf16_f32 v14, v14, v15
	v_cvt_pk_bf16_f32 v15, v16, v17
	global_store_dwordx2 v[54:55], v[18:19], off offset:1536 sc1
	global_store_dwordx2 v[56:57], v[14:15], off offset:1536 sc1
	s_waitcnt vmcnt(8)
	s_cbranch_scc0 .LBB0_57
